# grid barrier after MoE gate_up / down: every arriving workgroup issues an early buffer_wbl2 before its arrival atomic
# baseline (speedup 1.0000x reference)
; __device__ __forceinline__ unsigned xb_ld(unsigned* p)              { return __hip_atomic_load(p, __ATOMIC_RELAXED, __HIP_MEMORY_SCOPE_AGENT); }
; __device__ __forceinline__ unsigned xb_add(unsigned* p, unsigned v) { return __hip_atomic_fetch_add(p, v, __ATOMIC_RELAXED, __HIP_MEMORY_SCOPE_AGENT); }
; #define XB_SPIN(cond, bar) do { unsigned _sp = 0; while (cond) { __builtin_amdgcn_s_sleep(1); \
;     if ((++_sp & 255u) == 0u) { if (xb_ld(&(bar)[XB_TMO])) break; if (_sp > XB_SPIN_CAP) { atomicAdd(&(bar)[XB_TMO], 1u); break; } } } } while (0)
; __device__ __forceinline__ void xcd_barrier(const XcdBarrier& b, const bool is_t0) {
;     ...
;         unsigned nloc = b.st[0], nx = b.st[1];
;         if (nloc == 0u) { xcd_barrier_complete(bar, b.x, nloc, nx); b.st[0] = nloc; b.st[1] = nx; }
;         const unsigned old = xb_add(&bar[XB_XSUB(b.x)], 1u);
;         const unsigned gen = old / nloc;
;         if (old + 1u == (gen + 1u) * nloc) {
;             __builtin_amdgcn_fence(__ATOMIC_RELEASE, "agent");
;             asm volatile("s_waitcnt vmcnt(0)" ::: "memory");
;             const unsigned og = xb_add(&bar[XB_TOP], 1u);
;             const unsigned tg = og / nx;
;             if (og + 1u == (tg + 1u) * nx) xb_add(&bar[XB_TOPGEN], 1u);
;             else XB_SPIN(xb_ld(&bar[XB_TOPGEN]) == tg, bar);
;             __builtin_amdgcn_fence(__ATOMIC_ACQUIRE, "agent");
;             xb_add(&bar[XB_XGEN(b.x)], 1u);
;             asm volatile("s_waitcnt vmcnt(0)" ::: "memory");
;         } else {
;             XB_SPIN(xb_ld(&bar[XB_XGEN(b.x)]) == gen, bar);
.LBB0_2272:
	v_readlane_b32 s4, v250, 13
	v_readlane_b32 s5, v250, 14
	v_cvt_f32_u32_e32 v1, v3
	v_sub_u32_e32 v5, 0, v3
	v_rcp_iflag_f32_e32 v1, v1
	s_nop 1
	buffer_wbl2 sc1
	global_atomic_add v4, v199, v222, s[4:5] sc0
	v_mul_f32_e32 v1, 0x4f7ffffe, v1
	v_cvt_u32_f32_e32 v1, v1
	v_mul_lo_u32 v5, v5, v1
	v_mul_hi_u32 v5, v1, v5
	v_add_u32_e32 v1, v1, v5
	s_waitcnt vmcnt(0)
	v_mul_hi_u32 v1, v4, v1
	v_mul_lo_u32 v5, v1, v3
	v_sub_u32_e32 v5, v4, v5
	v_add_u32_e32 v6, 1, v1
	v_cmp_ge_u32_e32 vcc, v5, v3
	v_add_u32_e32 v4, 1, v4
	s_nop 0
	v_cndmask_b32_e32 v1, v1, v6, vcc
	v_sub_u32_e32 v6, v5, v3
	v_cndmask_b32_e32 v5, v5, v6, vcc
	v_add_u32_e32 v6, 1, v1
	v_cmp_ge_u32_e32 vcc, v5, v3
	s_nop 1
	v_cndmask_b32_e32 v1, v1, v6, vcc
	v_mul_lo_u32 v5, v3, v1
	v_add_u32_e32 v3, v5, v3
	v_cmp_ne_u32_e32 vcc, v4, v3
	s_and_saveexec_b64 s[4:5], vcc
	s_xor_b64 s[14:15], exec, s[4:5]
	s_cbranch_execz .LBB0_2286
	v_readlane_b32 s4, v250, 15
	v_readlane_b32 s5, v250, 16
	s_waitcnt lgkmcnt(0)
	s_nop 3
	global_load_dword v2, v199, s[4:5] sc1
	s_waitcnt vmcnt(0)
	v_cmp_eq_u32_e32 vcc, v2, v1
	s_and_saveexec_b64 s[26:27], vcc
	s_cbranch_execz .LBB0_2285
	s_mov_b32 s30, 1
	s_mov_b64 s[4:5], 0
	s_branch .LBB0_2276
